# attention unit epilogues: 16 dwordx2 row-per-lane stores widened to 8 dwordx4 via v_permlane32_swap pairs (guide 7.3), on top of S5 permlane transpose
# speedup vs baseline: 1.0091x; 1.0048x over previous
; __device__ __forceinline__ void store4(bf16_t* p, f32x4 v) { u32x2 w; w.x = pk2(v.x, v.y); w.y = pk2(v.z, v.w); *(u32x2*)p = w; }
; template <bool MLA>
; __device__ __forceinline__ void attn_unit(LAS unsigned char* lds, const bf16_t* Q, const bf16_t* Kp, const bf16_t* V, bf16_t* O, const float* ssq_qn, const float* ssq_qr, const float* cl, int b, int h, int qb) {
;     ...
;     const float lt = l_run + __shfl_xor(l_run, 32), inv = 1.f / lt;
;     bf16_t* op = O + qrow * 256 + h * 64 + 4 * hh;
; #pragma unroll
;     for (int g = 0; g < 4; ++g) {
;         store4(op + 8 * g, (f32x4){o0[4 * g] * inv, o0[4 * g + 1] * inv, o0[4 * g + 2] * inv, o0[4 * g + 3] * inv});
;         store4(op + 32 + 8 * g, (f32x4){o1[4 * g] * inv, o1[4 * g + 1] * inv, o1[4 * g + 2] * inv, o1[4 * g + 3] * inv});
;     }
.LBB0_343:
	ds_bpermute_b32 v36, v110, v108
	v_lshl_add_u64 v[34:35], s[0:1], 0, v[90:91]
	v_lshlrev_b32_e32 v0, 1, v103
	v_lshl_add_u64 v[34:35], v[34:35], 0, s[2:3]
	v_lshl_add_u64 v[34:35], v[34:35], 0, v[0:1]
	s_waitcnt lgkmcnt(0)
	v_add_f32_e32 v36, v108, v36
	v_div_scale_f32 v37, s[6:7], v36, v36, 1.0
	v_rcp_f32_e32 v38, v37
	v_div_scale_f32 v39, vcc, 1.0, v36, 1.0
	s_add_i32 s23, s23, s27
	v_fma_f32 v40, -v37, v38, 1.0
	v_fmac_f32_e32 v38, v40, v38
	v_mul_f32_e32 v40, v39, v38
	v_fma_f32 v41, -v37, v40, v39
	v_fmac_f32_e32 v40, v41, v38
	v_fma_f32 v37, -v37, v40, v39
	v_div_fmas_f32 v37, v37, v38, v40
	v_div_fixup_f32 v36, v37, v36, 1.0
	s_add_i32 s22, s22, s27
	s_cmpk_gt_i32 s23, 0xff
	v_and_b32_e32 v178, 32, v248
	v_mov_b32_e32 v179, 0
	v_lshrrev_b32_e32 v178, 2, v178
	v_lshl_add_u64 v[34:35], v[34:35], 0, v[178:179]
	v_pk_mul_f32 v[18:19], v[18:19], v[36:37] op_sel_hi:[1,0]
	v_pk_mul_f32 v[20:21], v[20:21], v[36:37] op_sel_hi:[1,0]
	v_pk_mul_f32 v[22:23], v[22:23], v[36:37] op_sel_hi:[1,0]
	v_pk_mul_f32 v[24:25], v[24:25], v[36:37] op_sel_hi:[1,0]
	v_cvt_pk_bf16_f32 v180, v18, v19
	v_cvt_pk_bf16_f32 v181, v20, v21
	v_cvt_pk_bf16_f32 v182, v22, v23
	v_cvt_pk_bf16_f32 v183, v24, v25
	s_nop 1
	v_permlane32_swap_b32_e32 v180, v182
	v_permlane32_swap_b32_e32 v181, v183
	global_store_dwordx4 v[34:35], v[180:183], off
	v_pk_mul_f32 v[26:27], v[26:27], v[36:37] op_sel_hi:[1,0]
	v_pk_mul_f32 v[28:29], v[28:29], v[36:37] op_sel_hi:[1,0]
	v_pk_mul_f32 v[30:31], v[30:31], v[36:37] op_sel_hi:[1,0]
	v_pk_mul_f32 v[32:33], v[32:33], v[36:37] op_sel_hi:[1,0]
	v_cvt_pk_bf16_f32 v184, v26, v27
	v_cvt_pk_bf16_f32 v185, v28, v29
	v_cvt_pk_bf16_f32 v186, v30, v31
	v_cvt_pk_bf16_f32 v187, v32, v33
	s_nop 1
	v_permlane32_swap_b32_e32 v184, v186
	v_permlane32_swap_b32_e32 v185, v187
	global_store_dwordx4 v[34:35], v[184:187], off offset:32
	v_pk_mul_f32 v[2:3], v[2:3], v[36:37] op_sel_hi:[1,0]
	v_pk_mul_f32 v[4:5], v[4:5], v[36:37] op_sel_hi:[1,0]
	v_pk_mul_f32 v[6:7], v[6:7], v[36:37] op_sel_hi:[1,0]
	v_pk_mul_f32 v[8:9], v[8:9], v[36:37] op_sel_hi:[1,0]
	v_cvt_pk_bf16_f32 v188, v2, v3
	v_cvt_pk_bf16_f32 v189, v4, v5
	v_cvt_pk_bf16_f32 v190, v6, v7
	v_cvt_pk_bf16_f32 v191, v8, v9
	s_nop 1
	v_permlane32_swap_b32_e32 v188, v190
	v_permlane32_swap_b32_e32 v189, v191
	global_store_dwordx4 v[34:35], v[188:191], off offset:64
	v_pk_mul_f32 v[10:11], v[10:11], v[36:37] op_sel_hi:[1,0]
	v_pk_mul_f32 v[12:13], v[12:13], v[36:37] op_sel_hi:[1,0]
	v_pk_mul_f32 v[14:15], v[14:15], v[36:37] op_sel_hi:[1,0]
	v_pk_mul_f32 v[16:17], v[16:17], v[36:37] op_sel_hi:[1,0]
	v_cvt_pk_bf16_f32 v232, v10, v11
	v_cvt_pk_bf16_f32 v233, v12, v13
	v_cvt_pk_bf16_f32 v234, v14, v15
	v_cvt_pk_bf16_f32 v235, v16, v17
	s_nop 1
	v_permlane32_swap_b32_e32 v232, v234
	v_permlane32_swap_b32_e32 v233, v235
	global_store_dwordx4 v[34:35], v[232:235], off offset:96
	s_cbranch_scc1 .LBB0_432

; __device__ __forceinline__ unsigned pk2(float lo, float hi) { f32x2 v = {lo, hi}; bf16x2_t b = __builtin_convertvector(v, bf16x2_t); return __builtin_bit_cast(unsigned, b); }
; __device__ __forceinline__ void store4(bf16_t* p, f32x4 v) { u32x2 w; w.x = pk2(v.x, v.y); w.y = pk2(v.z, v.w); *(u32x2*)p = w; }
; template <bool MLA>
; __device__ __forceinline__ void attn_unit(LAS unsigned char* lds, const bf16_t* Q, const bf16_t* Kp, const bf16_t* V, bf16_t* O, const float* ssq_qn, const float* ssq_qr, const float* cl, int b, int h, int qb) {
;     ...
;     const long qrow = rowb + qb * 256 + w * 32 + r;
;     bf16x8 qfr[NC];
; #pragma unroll
;     for (int c = 0; c < NC; ++c) qfr[c] = *(const bf16x8*)(Q + qrow * LDQ + h * DK + 16 * c + 8 * hh);
;     if (MLA) {
;         const float s = rsqrtf((ssq_qn[qrow * 4 + h] + ssq_qr[qrow * 4 + h]) * (1.f / 96.f) + EPS) * (0.10206207261596574f * LOG2E);
; #pragma unroll
;         for (int c = 0; c < NC; ++c) { u32x4 wv = __builtin_bit_cast(u32x4, qfr[c]);
; #pragma unroll
;             for (int j = 0; j < 4; ++j) wv[j] = pk2(__uint_as_float(wv[j] << 16) * s, __uint_as_float(wv[j] & 0xffff0000u) * s);
;             qfr[c] = __builtin_bit_cast(bf16x8, wv); }
;     }
;     const int ntile = 4 * (qb + 1);
;     const int tq_lo = qb * 256 + w * 32, tq = tq_lo + r, tq_hi = tq_lo + 31;
;     float m_run = -1e30f, l_run = 0.f;
;     f32x16 o0, o1;
; #pragma unroll
;     for (int i = 0; i < 16; ++i) { o0[i] = 0.f; o1[i] = 0.f; }
;     u32x4 kst0, kst1 = (u32x4){0, 0, 0, 0}, vst; float cst = 0.f;
;     const int kr0 = tid / KSEG, ksg0 = tid % KSEG, kr1 = (tid + 512) / KSEG, ksg1 = (tid + 512) % KSEG;
;     const int vkv = tid >> 3, vds = tid & 7;
;     const bf16_t* kq0 = Kp + (rowb + kr0) * LDQ + h * DK + 8 * ksg0; const bf16_t* kq1 = Kp + (rowb + kr1) * LDQ + h * DK + 8 * ksg1;
;     const bf16_t* vq = V + (rowb + vkv) * 256 + h * 64 + 8 * vds; const float* cq_ = cl + (rowb + (tid & 63)) * 4 + h;
;     ...
;     const float lt = l_run + __shfl_xor(l_run, 32), inv = 1.f / lt;
;     bf16_t* op = O + qrow * 256 + h * 64 + 4 * hh;
; #pragma unroll
;     for (int g = 0; g < 4; ++g) {
;         store4(op + 8 * g, (f32x4){o0[4 * g] * inv, o0[4 * g + 1] * inv, o0[4 * g + 2] * inv, o0[4 * g + 3] * inv});
;         store4(op + 32 + 8 * g, (f32x4){o1[4 * g] * inv, o1[4 * g + 1] * inv, o1[4 * g + 2] * inv, o1[4 * g + 3] * inv});
;     }
.LBB0_366:
	v_and_b32_e32 v34, 64, v248
	v_xor_b32_e32 v0, 32, v248
	v_add_u32_e32 v34, 64, v34
	v_cmp_lt_i32_e32 vcc, v0, v34
	s_lshl_b32 s2, s2, 1
	s_lshl_b32 s16, s31, 2
	v_cndmask_b32_e32 v0, v248, v0, vcc
	v_lshlrev_b32_e32 v110, 2, v0
	ds_bpermute_b32 v0, v110, v121
	s_mov_b32 s17, s3
	v_mov_b32_e32 v98, 0
	s_waitcnt lgkmcnt(0)
	v_add_f32_e32 v0, v121, v0
	v_div_scale_f32 v34, s[8:9], v0, v0, 1.0
	v_rcp_f32_e32 v35, v34
	v_readlane_b32 s8, v255, 25
	v_readlane_b32 s9, v255, 26
	v_fma_f32 v36, -v34, v35, 1.0
	v_fmac_f32_e32 v35, v36, v35
	v_div_scale_f32 v36, vcc, 1.0, v0, 1.0
	v_mul_f32_e32 v37, v36, v35
	v_fma_f32 v38, -v34, v37, v36
	v_fmac_f32_e32 v37, v38, v35
	v_fma_f32 v34, -v34, v37, v36
	v_div_fmas_f32 v34, v34, v35, v37
	v_lshlrev_b64 v[36:37], 9, v[102:103]
	v_div_fixup_f32 v34, v34, v0, 1.0
	v_lshl_add_u64 v[36:37], s[4:5], 0, v[36:37]
	v_lshl_add_u64 v[36:37], v[36:37], 0, s[2:3]
	v_lshlrev_b32_e32 v0, 1, v114
	v_lshl_add_u64 v[36:37], v[36:37], 0, v[0:1]
	v_and_b32_e32 v178, 32, v248
	v_mov_b32_e32 v179, 0
	v_lshrrev_b32_e32 v178, 2, v178
	v_lshl_add_u64 v[36:37], v[36:37], 0, v[178:179]
	v_pk_mul_f32 v[18:19], v[18:19], v[34:35] op_sel_hi:[1,0]
	v_pk_mul_f32 v[20:21], v[20:21], v[34:35] op_sel_hi:[1,0]
	v_pk_mul_f32 v[22:23], v[22:23], v[34:35] op_sel_hi:[1,0]
	v_pk_mul_f32 v[24:25], v[24:25], v[34:35] op_sel_hi:[1,0]
	v_cvt_pk_bf16_f32 v180, v18, v19
	v_cvt_pk_bf16_f32 v181, v20, v21
	v_cvt_pk_bf16_f32 v182, v22, v23
	v_cvt_pk_bf16_f32 v183, v24, v25
	s_nop 1
	v_permlane32_swap_b32_e32 v180, v182
	v_permlane32_swap_b32_e32 v181, v183
	global_store_dwordx4 v[36:37], v[180:183], off
	v_pk_mul_f32 v[26:27], v[26:27], v[34:35] op_sel_hi:[1,0]
	v_pk_mul_f32 v[28:29], v[28:29], v[34:35] op_sel_hi:[1,0]
	v_pk_mul_f32 v[30:31], v[30:31], v[34:35] op_sel_hi:[1,0]
	v_pk_mul_f32 v[32:33], v[32:33], v[34:35] op_sel_hi:[1,0]
	v_cvt_pk_bf16_f32 v184, v26, v27
	v_cvt_pk_bf16_f32 v185, v28, v29
	v_cvt_pk_bf16_f32 v186, v30, v31
	v_cvt_pk_bf16_f32 v187, v32, v33
	s_nop 1
	v_permlane32_swap_b32_e32 v184, v186
	v_permlane32_swap_b32_e32 v185, v187
	global_store_dwordx4 v[36:37], v[184:187], off offset:32
	v_pk_mul_f32 v[2:3], v[2:3], v[34:35] op_sel_hi:[1,0]
	v_pk_mul_f32 v[4:5], v[4:5], v[34:35] op_sel_hi:[1,0]
	v_pk_mul_f32 v[6:7], v[6:7], v[34:35] op_sel_hi:[1,0]
	v_pk_mul_f32 v[8:9], v[8:9], v[34:35] op_sel_hi:[1,0]
	v_cvt_pk_bf16_f32 v188, v2, v3
	v_cvt_pk_bf16_f32 v189, v4, v5
	v_cvt_pk_bf16_f32 v190, v6, v7
	v_cvt_pk_bf16_f32 v191, v8, v9
	s_nop 1
	v_permlane32_swap_b32_e32 v188, v190
	v_permlane32_swap_b32_e32 v189, v191
	global_store_dwordx4 v[36:37], v[188:191], off offset:64
	v_pk_mul_f32 v[10:11], v[10:11], v[34:35] op_sel_hi:[1,0]
	v_pk_mul_f32 v[12:13], v[12:13], v[34:35] op_sel_hi:[1,0]
	v_pk_mul_f32 v[14:15], v[14:15], v[34:35] op_sel_hi:[1,0]
	v_pk_mul_f32 v[16:17], v[16:17], v[34:35] op_sel_hi:[1,0]
	v_cvt_pk_bf16_f32 v232, v10, v11
	v_cvt_pk_bf16_f32 v233, v12, v13
	v_cvt_pk_bf16_f32 v234, v14, v15
	v_cvt_pk_bf16_f32 v235, v16, v17
	s_nop 1
	v_permlane32_swap_b32_e32 v232, v234
	v_permlane32_swap_b32_e32 v233, v235
	global_store_dwordx4 v[36:37], v[232:235], off offset:96
	v_mov_b32_e32 v14, v195
	v_mov_b32_e32 v19, s7
	v_and_b32_e32 v17, 31, v14
	v_ashrrev_i32_e32 v0, 1, v14
	v_and_b32_e32 v2, 0xffffffe0, v0
	v_or_b32_e32 v0, s34, v17
	v_ashrrev_i32_e32 v3, 31, v2
	v_or_b32_e32 v18, s6, v0
	v_lshl_add_u64 v[4:5], v[18:19], 0, v[2:3]
	v_ashrrev_i32_e32 v3, 31, v14
	v_lshlrev_b64 v[90:91], 9, v[4:5]
	v_lshrrev_b32_e32 v3, 29, v3
	v_bfe_u32 v16, v14, 5, 1
	v_lshl_add_u64 v[4:5], s[58:59], 0, v[90:91]
	v_add_u32_e32 v3, v14, v3
	v_lshl_add_u64 v[4:5], v[4:5], 0, s[2:3]
	v_lshlrev_b32_e32 v0, 4, v16
	v_ashrrev_i32_e32 v10, 3, v3
	v_lshl_add_u64 v[4:5], v[4:5], 0, v[0:1]
	v_ashrrev_i32_e32 v11, 31, v10
	global_load_dwordx4 v[66:69], v[4:5], off
	global_load_dwordx4 v[70:73], v[4:5], off offset:32
	global_load_dwordx4 v[74:77], v[4:5], off offset:64
	global_load_dwordx4 v[78:81], v[4:5], off offset:96
	v_and_b32_e32 v3, -8, v3
	v_lshl_add_u64 v[4:5], s[6:7], 0, v[10:11]
	v_sub_u32_e32 v3, v14, v3
	v_lshlrev_b64 v[4:5], 9, v[4:5]
	v_ashrrev_i32_e32 v8, 3, v14
	v_lshl_add_u64 v[4:5], s[60:61], 0, v[4:5]
	v_lshlrev_b32_e32 v6, 3, v3
	v_lshl_add_u64 v[4:5], v[4:5], 0, s[2:3]
	v_ashrrev_i32_e32 v7, 31, v6
	v_ashrrev_i32_e32 v9, 31, v8
	v_lshl_add_u64 v[4:5], v[6:7], 1, v[4:5]
	v_lshl_add_u64 v[6:7], s[6:7], 0, v[8:9]
	v_lshlrev_b64 v[6:7], 9, v[6:7]
	v_and_b32_e32 v12, 7, v14
	v_lshl_add_u64 v[6:7], s[8:9], 0, v[6:7]
	v_lshl_add_u64 v[6:7], v[6:7], 0, s[2:3]
	v_lshlrev_b32_e32 v12, 4, v12
	v_mov_b32_e32 v13, v1
	v_lshl_add_u64 v[6:7], v[6:7], 0, v[12:13]
	global_load_dwordx4 v[82:85], v[4:5], off
	global_load_dwordx4 v[86:89], v[6:7], off
	v_and_b32_e32 v15, 63, v14
	v_or_b32_e32 v18, s6, v15
	v_lshl_add_u64 v[18:19], v[18:19], 4, s[44:45]
	v_lshl_add_u64 v[92:93], v[18:19], 0, s[16:17]
	v_cmp_lt_i32_e32 vcc, 63, v14
	v_cmp_gt_i32_e64 s[38:39], 64, v14
	s_and_saveexec_b64 s[8:9], s[38:39]
	s_cbranch_execz .LBB0_368
	global_load_dword v9, v[92:93], off
	v_lshl_add_u64 v[92:93], v[92:93], 0, s[78:79]
	s_waitcnt vmcnt(0)
	v_xor_b32_e32 v98, 0x80000000, v9

; __device__ __forceinline__ unsigned pk2(float lo, float hi) { f32x2 v = {lo, hi}; bf16x2_t b = __builtin_convertvector(v, bf16x2_t); return __builtin_bit_cast(unsigned, b); }
; __device__ __forceinline__ void store4(bf16_t* p, f32x4 v) { u32x2 w; w.x = pk2(v.x, v.y); w.y = pk2(v.z, v.w); *(u32x2*)p = w; }
; template <bool MLA>
; __device__ __forceinline__ void attn_unit(LAS unsigned char* lds, const bf16_t* Q, const bf16_t* Kp, const bf16_t* V, bf16_t* O, const float* ssq_qn, const float* ssq_qr, const float* cl, int b, int h, int qb) {
;     ...
;     const long qrow = rowb + qb * 256 + w * 32 + r;
;     bf16x8 qfr[NC];
; #pragma unroll
;     for (int c = 0; c < NC; ++c) qfr[c] = *(const bf16x8*)(Q + qrow * LDQ + h * DK + 16 * c + 8 * hh);
;     if (MLA) {
;         const float s = rsqrtf((ssq_qn[qrow * 4 + h] + ssq_qr[qrow * 4 + h]) * (1.f / 96.f) + EPS) * (0.10206207261596574f * LOG2E);
; #pragma unroll
;         for (int c = 0; c < NC; ++c) { u32x4 wv = __builtin_bit_cast(u32x4, qfr[c]);
; #pragma unroll
;             for (int j = 0; j < 4; ++j) wv[j] = pk2(__uint_as_float(wv[j] << 16) * s, __uint_as_float(wv[j] & 0xffff0000u) * s);
;             qfr[c] = __builtin_bit_cast(bf16x8, wv); }
;     }
;     const int ntile = 4 * (qb + 1);
;     const int tq_lo = qb * 256 + w * 32, tq = tq_lo + r, tq_hi = tq_lo + 31;
;     float m_run = -1e30f, l_run = 0.f;
;     f32x16 o0, o1;
; #pragma unroll
;     for (int i = 0; i < 16; ++i) { o0[i] = 0.f; o1[i] = 0.f; }
;     u32x4 kst0, kst1 = (u32x4){0, 0, 0, 0}, vst; float cst = 0.f;
;     const int kr0 = tid / KSEG, ksg0 = tid % KSEG, kr1 = (tid + 512) / KSEG, ksg1 = (tid + 512) % KSEG;
;     const int vkv = tid >> 3, vds = tid & 7;
;     const bf16_t* kq0 = Kp + (rowb + kr0) * LDQ + h * DK + 8 * ksg0; const bf16_t* kq1 = Kp + (rowb + kr1) * LDQ + h * DK + 8 * ksg1;
;     const bf16_t* vq = V + (rowb + vkv) * 256 + h * 64 + 8 * vds; const float* cq_ = cl + (rowb + (tid & 63)) * 4 + h;
;     ...
;     const float lt = l_run + __shfl_xor(l_run, 32), inv = 1.f / lt;
;     bf16_t* op = O + qrow * 256 + h * 64 + 4 * hh;
; #pragma unroll
;     for (int g = 0; g < 4; ++g) {
;         store4(op + 8 * g, (f32x4){o0[4 * g] * inv, o0[4 * g + 1] * inv, o0[4 * g + 2] * inv, o0[4 * g + 3] * inv});
;         store4(op + 32 + 8 * g, (f32x4){o1[4 * g] * inv, o1[4 * g + 1] * inv, o1[4 * g + 2] * inv, o1[4 * g + 3] * inv});
;     }
.LBB0_388:
	ds_bpermute_b32 v36, v110, v108
	v_lshl_add_u64 v[34:35], s[0:1], 0, v[90:91]
	v_lshlrev_b32_e32 v0, 1, v103
	v_lshl_add_u64 v[34:35], v[34:35], 0, s[2:3]
	v_lshl_add_u64 v[34:35], v[34:35], 0, v[0:1]
	s_waitcnt lgkmcnt(0)
	v_add_f32_e32 v36, v108, v36
	v_div_scale_f32 v37, s[8:9], v36, v36, 1.0
	v_rcp_f32_e32 v38, v37
	v_div_scale_f32 v39, vcc, 1.0, v36, 1.0
	s_lshl_b32 s34, s30, 8
	v_fma_f32 v40, -v37, v38, 1.0
	v_fmac_f32_e32 v38, v40, v38
	v_mul_f32_e32 v40, v39, v38
	v_fma_f32 v41, -v37, v40, v39
	v_fmac_f32_e32 v40, v41, v38
	v_fma_f32 v37, -v37, v40, v39
	v_div_fmas_f32 v37, v37, v38, v40
	v_div_fixup_f32 v36, v37, v36, 1.0
	v_mov_b32_e32 v40, v195
	v_and_b32_e32 v178, 32, v248
	v_mov_b32_e32 v179, 0
	v_lshrrev_b32_e32 v178, 2, v178
	v_lshl_add_u64 v[34:35], v[34:35], 0, v[178:179]
	v_pk_mul_f32 v[18:19], v[18:19], v[36:37] op_sel_hi:[1,0]
	v_pk_mul_f32 v[20:21], v[20:21], v[36:37] op_sel_hi:[1,0]
	v_pk_mul_f32 v[22:23], v[22:23], v[36:37] op_sel_hi:[1,0]
	v_pk_mul_f32 v[24:25], v[24:25], v[36:37] op_sel_hi:[1,0]
	v_cvt_pk_bf16_f32 v180, v18, v19
	v_cvt_pk_bf16_f32 v181, v20, v21
	v_cvt_pk_bf16_f32 v182, v22, v23
	v_cvt_pk_bf16_f32 v183, v24, v25
	s_nop 1
	v_permlane32_swap_b32_e32 v180, v182
	v_permlane32_swap_b32_e32 v181, v183
	global_store_dwordx4 v[34:35], v[180:183], off
	v_pk_mul_f32 v[26:27], v[26:27], v[36:37] op_sel_hi:[1,0]
	v_pk_mul_f32 v[28:29], v[28:29], v[36:37] op_sel_hi:[1,0]
	v_pk_mul_f32 v[30:31], v[30:31], v[36:37] op_sel_hi:[1,0]
	v_pk_mul_f32 v[32:33], v[32:33], v[36:37] op_sel_hi:[1,0]
	v_cvt_pk_bf16_f32 v184, v26, v27
	v_cvt_pk_bf16_f32 v185, v28, v29
	v_cvt_pk_bf16_f32 v186, v30, v31
	v_cvt_pk_bf16_f32 v187, v32, v33
	s_nop 1
	v_permlane32_swap_b32_e32 v184, v186
	v_permlane32_swap_b32_e32 v185, v187
	global_store_dwordx4 v[34:35], v[184:187], off offset:32
	v_pk_mul_f32 v[2:3], v[2:3], v[36:37] op_sel_hi:[1,0]
	v_pk_mul_f32 v[4:5], v[4:5], v[36:37] op_sel_hi:[1,0]
	v_pk_mul_f32 v[6:7], v[6:7], v[36:37] op_sel_hi:[1,0]
	v_pk_mul_f32 v[8:9], v[8:9], v[36:37] op_sel_hi:[1,0]
	v_cvt_pk_bf16_f32 v188, v2, v3
	v_cvt_pk_bf16_f32 v189, v4, v5
	v_cvt_pk_bf16_f32 v190, v6, v7
	v_cvt_pk_bf16_f32 v191, v8, v9
	s_nop 1
	v_permlane32_swap_b32_e32 v188, v190
	v_permlane32_swap_b32_e32 v189, v191
	global_store_dwordx4 v[34:35], v[188:191], off offset:64
	v_pk_mul_f32 v[10:11], v[10:11], v[36:37] op_sel_hi:[1,0]
	v_pk_mul_f32 v[12:13], v[12:13], v[36:37] op_sel_hi:[1,0]
	v_pk_mul_f32 v[14:15], v[14:15], v[36:37] op_sel_hi:[1,0]
	v_pk_mul_f32 v[16:17], v[16:17], v[36:37] op_sel_hi:[1,0]
	v_cvt_pk_bf16_f32 v232, v10, v11
	v_cvt_pk_bf16_f32 v233, v12, v13
	v_cvt_pk_bf16_f32 v234, v14, v15
	v_cvt_pk_bf16_f32 v235, v16, v17
	s_nop 1
	v_permlane32_swap_b32_e32 v232, v234
	v_permlane32_swap_b32_e32 v233, v235
	global_store_dwordx4 v[34:35], v[232:235], off offset:96
	v_mov_b32_e32 v3, s7
	v_and_b32_e32 v42, 31, v40
	v_ashrrev_i32_e32 v0, 1, v40
	v_and_b32_e32 v28, 0xffffffe0, v0
	v_or_b32_e32 v0, s34, v42
	v_ashrrev_i32_e32 v29, 31, v28
	v_or_b32_e32 v2, s6, v0
	v_lshl_add_u64 v[102:103], v[2:3], 0, v[28:29]
	v_mov_b64_e32 v[2:3], s[70:71]
	s_movk_i32 s13, 0x300
	v_mad_u64_u32 v[2:3], s[8:9], v102, s13, v[2:3]
	v_bfe_u32 v41, v40, 5, 1
	v_mad_i32_i24 v3, v103, s13, v3
	s_mov_b32 s15, s3
	v_lshlrev_b64 v[4:5], 4, v[102:103]
	v_lshl_add_u64 v[2:3], v[2:3], 0, s[14:15]
	v_lshlrev_b32_e32 v30, 4, v41
	v_mov_b32_e32 v31, v1
	v_lshl_or_b32 v4, s31, 2, v4
	s_mov_b32 s12, 0x2aaaaaab
	v_lshl_add_u64 v[2:3], v[2:3], 0, v[30:31]
	v_lshl_add_u64 v[24:25], s[66:67], 0, v[4:5]
	v_mul_hi_i32 v0, v40, s12
	global_load_dwordx4 v[20:23], v[2:3], off offset:32
	global_load_dwordx4 v[16:19], v[2:3], off offset:64
	global_load_dwordx4 v[12:15], v[2:3], off offset:96
	global_load_dwordx4 v[8:11], v[2:3], off offset:128
	v_lshl_add_u64 v[26:27], s[68:69], 0, v[4:5]
	global_load_dwordx4 v[4:7], v[2:3], off offset:160
	global_load_dword v29, v[24:25], off
	global_load_dword v31, v[26:27], off
	v_lshrrev_b32_e32 v24, 31, v0
	v_ashrrev_i32_e32 v0, 1, v0
	v_add_u32_e32 v34, v0, v24
	v_ashrrev_i32_e32 v35, 31, v34
	v_lshl_add_u64 v[24:25], s[6:7], 0, v[34:35]
	v_mov_b64_e32 v[38:39], s[46:47]
	v_mul_lo_u32 v0, v34, 12
	v_mad_u64_u32 v[26:27], s[8:9], v24, s13, v[38:39]
	v_sub_u32_e32 v43, v40, v0
	v_mad_i32_i24 v27, v25, s13, v27
	v_lshl_add_u64 v[24:25], v[26:27], 0, s[14:15]
	v_lshlrev_b32_e32 v26, 3, v43
	v_ashrrev_i32_e32 v27, 31, v26
	v_lshl_add_u64 v[32:33], v[26:27], 1, v[24:25]
	global_load_dwordx4 v[24:27], v[2:3], off
	global_load_dwordx4 v[66:69], v[32:33], off
	v_add_u32_e32 v0, 0x200, v40
	v_mul_hi_i32 v2, v0, s12
	v_lshrrev_b32_e32 v3, 31, v2
	v_ashrrev_i32_e32 v2, 1, v2
	v_add_u32_e32 v36, v2, v3
	v_mul_lo_u32 v2, v36, 12
	v_ashrrev_i32_e32 v37, 31, v36
	v_sub_u32_e32 v35, v0, v2
	v_lshl_add_u64 v[2:3], s[6:7], 0, v[36:37]
	v_mad_u64_u32 v[38:39], s[8:9], v2, s13, v[38:39]
	v_mad_i32_i24 v39, v3, s13, v39
	v_lshl_add_u64 v[2:3], v[38:39], 0, s[14:15]
	v_lshlrev_b32_e32 v38, 3, v35
	v_ashrrev_i32_e32 v39, 31, v38
	v_lshl_add_u64 v[104:105], v[38:39], 1, v[2:3]
	v_mov_b32_e32 v2, v1
	v_mov_b32_e32 v3, v1
	s_movk_i32 s8, 0x100
	v_mov_b32_e32 v0, v1
	v_mov_b64_e32 v[72:73], v[2:3]
	v_cmp_lt_i32_e32 vcc, s73, v40
	v_cmp_gt_i32_e64 s[38:39], s8, v40
	v_mov_b64_e32 v[70:71], v[0:1]
	s_and_saveexec_b64 s[8:9], s[38:39]
	s_cbranch_execz .LBB0_390
	global_load_dwordx4 v[70:73], v[104:105], off
	v_lshl_add_u64 v[104:105], v[104:105], 0, s[24:25]

; __device__ __forceinline__ unsigned pk2(float lo, float hi) { f32x2 v = {lo, hi}; bf16x2_t b = __builtin_convertvector(v, bf16x2_t); return __builtin_bit_cast(unsigned, b); }
; __device__ __forceinline__ void store4(bf16_t* p, f32x4 v) { u32x2 w; w.x = pk2(v.x, v.y); w.y = pk2(v.z, v.w); *(u32x2*)p = w; }
; template <bool MLA>
; __device__ __forceinline__ void attn_unit(LAS unsigned char* lds, const bf16_t* Q, const bf16_t* Kp, const bf16_t* V, bf16_t* O, const float* ssq_qn, const float* ssq_qr, const float* cl, int b, int h, int qb) {
;     ...
;     const long qrow = rowb + qb * 256 + w * 32 + r;
;     bf16x8 qfr[NC];
; #pragma unroll
;     for (int c = 0; c < NC; ++c) qfr[c] = *(const bf16x8*)(Q + qrow * LDQ + h * DK + 16 * c + 8 * hh);
;     if (MLA) {
;         const float s = rsqrtf((ssq_qn[qrow * 4 + h] + ssq_qr[qrow * 4 + h]) * (1.f / 96.f) + EPS) * (0.10206207261596574f * LOG2E);
; #pragma unroll
;         for (int c = 0; c < NC; ++c) { u32x4 wv = __builtin_bit_cast(u32x4, qfr[c]);
; #pragma unroll
;             for (int j = 0; j < 4; ++j) wv[j] = pk2(__uint_as_float(wv[j] << 16) * s, __uint_as_float(wv[j] & 0xffff0000u) * s);
;             qfr[c] = __builtin_bit_cast(bf16x8, wv); }
;     }
;     const int ntile = 4 * (qb + 1);
;     const int tq_lo = qb * 256 + w * 32, tq = tq_lo + r, tq_hi = tq_lo + 31;
;     float m_run = -1e30f, l_run = 0.f;
;     f32x16 o0, o1;
; #pragma unroll
;     for (int i = 0; i < 16; ++i) { o0[i] = 0.f; o1[i] = 0.f; }
;     u32x4 kst0, kst1 = (u32x4){0, 0, 0, 0}, vst; float cst = 0.f;
;     const int kr0 = tid / KSEG, ksg0 = tid % KSEG, kr1 = (tid + 512) / KSEG, ksg1 = (tid + 512) % KSEG;
;     const int vkv = tid >> 3, vds = tid & 7;
;     const bf16_t* kq0 = Kp + (rowb + kr0) * LDQ + h * DK + 8 * ksg0; const bf16_t* kq1 = Kp + (rowb + kr1) * LDQ + h * DK + 8 * ksg1;
;     const bf16_t* vq = V + (rowb + vkv) * 256 + h * 64 + 8 * vds; const float* cq_ = cl + (rowb + (tid & 63)) * 4 + h;
;     ...
;     const float lt = l_run + __shfl_xor(l_run, 32), inv = 1.f / lt;
;     bf16_t* op = O + qrow * 256 + h * 64 + 4 * hh;
; #pragma unroll
;     for (int g = 0; g < 4; ++g) {
;         store4(op + 8 * g, (f32x4){o0[4 * g] * inv, o0[4 * g + 1] * inv, o0[4 * g + 2] * inv, o0[4 * g + 3] * inv});
;         store4(op + 32 + 8 * g, (f32x4){o1[4 * g] * inv, o1[4 * g + 1] * inv, o1[4 * g + 2] * inv, o1[4 * g + 3] * inv});
;     }
.LBB0_410:
	ds_bpermute_b32 v0, v110, v122
	s_mov_b32 s17, s3
	v_mov_b32_e32 v98, 0
	s_waitcnt lgkmcnt(0)
	v_add_f32_e32 v0, v122, v0
	v_div_scale_f32 v34, s[8:9], v0, v0, 1.0
	v_rcp_f32_e32 v35, v34
	v_readlane_b32 s8, v255, 25
	v_readlane_b32 s9, v255, 26
	v_fma_f32 v36, -v34, v35, 1.0
	v_fmac_f32_e32 v35, v36, v35
	v_div_scale_f32 v36, vcc, 1.0, v0, 1.0
	v_mul_f32_e32 v37, v36, v35
	v_fma_f32 v38, -v34, v37, v36
	v_fmac_f32_e32 v37, v38, v35
	v_fma_f32 v34, -v34, v37, v36
	v_div_fmas_f32 v34, v34, v35, v37
	v_lshlrev_b64 v[36:37], 9, v[102:103]
	v_div_fixup_f32 v34, v34, v0, 1.0
	v_lshl_add_u64 v[36:37], s[4:5], 0, v[36:37]
	v_lshl_add_u64 v[36:37], v[36:37], 0, s[2:3]
	v_lshlrev_b32_e32 v0, 1, v115
	v_lshl_add_u64 v[36:37], v[36:37], 0, v[0:1]
	v_and_b32_e32 v178, 32, v248
	v_mov_b32_e32 v179, 0
	v_lshrrev_b32_e32 v178, 2, v178
	v_lshl_add_u64 v[36:37], v[36:37], 0, v[178:179]
	v_pk_mul_f32 v[18:19], v[18:19], v[34:35] op_sel_hi:[1,0]
	v_pk_mul_f32 v[20:21], v[20:21], v[34:35] op_sel_hi:[1,0]
	v_pk_mul_f32 v[22:23], v[22:23], v[34:35] op_sel_hi:[1,0]
	v_pk_mul_f32 v[24:25], v[24:25], v[34:35] op_sel_hi:[1,0]
	v_cvt_pk_bf16_f32 v180, v18, v19
	v_cvt_pk_bf16_f32 v181, v20, v21
	v_cvt_pk_bf16_f32 v182, v22, v23
	v_cvt_pk_bf16_f32 v183, v24, v25
	s_nop 1
	v_permlane32_swap_b32_e32 v180, v182
	v_permlane32_swap_b32_e32 v181, v183
	global_store_dwordx4 v[36:37], v[180:183], off
	v_pk_mul_f32 v[26:27], v[26:27], v[34:35] op_sel_hi:[1,0]
	v_pk_mul_f32 v[28:29], v[28:29], v[34:35] op_sel_hi:[1,0]
	v_pk_mul_f32 v[30:31], v[30:31], v[34:35] op_sel_hi:[1,0]
	v_pk_mul_f32 v[32:33], v[32:33], v[34:35] op_sel_hi:[1,0]
	v_cvt_pk_bf16_f32 v184, v26, v27
	v_cvt_pk_bf16_f32 v185, v28, v29
	v_cvt_pk_bf16_f32 v186, v30, v31
	v_cvt_pk_bf16_f32 v187, v32, v33
	s_nop 1
	v_permlane32_swap_b32_e32 v184, v186
	v_permlane32_swap_b32_e32 v185, v187
	global_store_dwordx4 v[36:37], v[184:187], off offset:32
	v_pk_mul_f32 v[2:3], v[2:3], v[34:35] op_sel_hi:[1,0]
	v_pk_mul_f32 v[4:5], v[4:5], v[34:35] op_sel_hi:[1,0]
	v_pk_mul_f32 v[6:7], v[6:7], v[34:35] op_sel_hi:[1,0]
	v_pk_mul_f32 v[8:9], v[8:9], v[34:35] op_sel_hi:[1,0]
	v_cvt_pk_bf16_f32 v188, v2, v3
	v_cvt_pk_bf16_f32 v189, v4, v5
	v_cvt_pk_bf16_f32 v190, v6, v7
	v_cvt_pk_bf16_f32 v191, v8, v9
	s_nop 1
	v_permlane32_swap_b32_e32 v188, v190
	v_permlane32_swap_b32_e32 v189, v191
	global_store_dwordx4 v[36:37], v[188:191], off offset:64
	v_pk_mul_f32 v[10:11], v[10:11], v[34:35] op_sel_hi:[1,0]
	v_pk_mul_f32 v[12:13], v[12:13], v[34:35] op_sel_hi:[1,0]
	v_pk_mul_f32 v[14:15], v[14:15], v[34:35] op_sel_hi:[1,0]
	v_pk_mul_f32 v[16:17], v[16:17], v[34:35] op_sel_hi:[1,0]
	v_cvt_pk_bf16_f32 v232, v10, v11
	v_cvt_pk_bf16_f32 v233, v12, v13
	v_cvt_pk_bf16_f32 v234, v14, v15
	v_cvt_pk_bf16_f32 v235, v16, v17
	s_nop 1
	v_permlane32_swap_b32_e32 v232, v234
	v_permlane32_swap_b32_e32 v233, v235
	global_store_dwordx4 v[36:37], v[232:235], off offset:96
	v_mov_b32_e32 v14, v195
	v_mov_b32_e32 v19, s7
	v_and_b32_e32 v17, 31, v14
	v_ashrrev_i32_e32 v0, 1, v14
	v_and_b32_e32 v2, 0xffffffe0, v0
	v_or_b32_e32 v0, s34, v17
	v_ashrrev_i32_e32 v3, 31, v2
	v_or_b32_e32 v18, s6, v0
	v_lshl_add_u64 v[4:5], v[18:19], 0, v[2:3]
	v_ashrrev_i32_e32 v3, 31, v14
	v_lshlrev_b64 v[90:91], 9, v[4:5]
	v_lshrrev_b32_e32 v3, 29, v3
	v_bfe_u32 v16, v14, 5, 1
	v_lshl_add_u64 v[4:5], s[58:59], 0, v[90:91]
	v_add_u32_e32 v3, v14, v3
	v_lshl_add_u64 v[4:5], v[4:5], 0, s[2:3]
	v_lshlrev_b32_e32 v0, 4, v16
	v_ashrrev_i32_e32 v10, 3, v3
	v_lshl_add_u64 v[4:5], v[4:5], 0, v[0:1]
	v_ashrrev_i32_e32 v11, 31, v10
	global_load_dwordx4 v[66:69], v[4:5], off
	global_load_dwordx4 v[70:73], v[4:5], off offset:32
	global_load_dwordx4 v[74:77], v[4:5], off offset:64
	global_load_dwordx4 v[78:81], v[4:5], off offset:96
	v_and_b32_e32 v3, -8, v3
	v_lshl_add_u64 v[4:5], s[6:7], 0, v[10:11]
	v_sub_u32_e32 v3, v14, v3
	v_lshlrev_b64 v[4:5], 9, v[4:5]
	v_ashrrev_i32_e32 v8, 3, v14
	v_lshl_add_u64 v[4:5], s[60:61], 0, v[4:5]
	v_lshlrev_b32_e32 v6, 3, v3
	v_lshl_add_u64 v[4:5], v[4:5], 0, s[2:3]
	v_ashrrev_i32_e32 v7, 31, v6
	v_ashrrev_i32_e32 v9, 31, v8
	v_lshl_add_u64 v[4:5], v[6:7], 1, v[4:5]
	v_lshl_add_u64 v[6:7], s[6:7], 0, v[8:9]
	v_lshlrev_b64 v[6:7], 9, v[6:7]
	v_and_b32_e32 v12, 7, v14
	v_lshl_add_u64 v[6:7], s[8:9], 0, v[6:7]
	v_lshl_add_u64 v[6:7], v[6:7], 0, s[2:3]
	v_lshlrev_b32_e32 v12, 4, v12
	v_mov_b32_e32 v13, v1
	v_lshl_add_u64 v[6:7], v[6:7], 0, v[12:13]
	global_load_dwordx4 v[82:85], v[4:5], off
	global_load_dwordx4 v[86:89], v[6:7], off
	v_and_b32_e32 v15, 63, v14
	v_or_b32_e32 v18, s6, v15
	v_lshl_add_u64 v[18:19], v[18:19], 4, s[44:45]
	v_lshl_add_u64 v[92:93], v[18:19], 0, s[16:17]
	v_cmp_lt_i32_e32 vcc, 63, v14
	v_cmp_gt_i32_e64 s[38:39], 64, v14
	s_and_saveexec_b64 s[6:7], s[38:39]
	s_cbranch_execz .LBB0_412
	global_load_dword v9, v[92:93], off
	v_lshl_add_u64 v[92:93], v[92:93], 0, s[78:79]
	s_waitcnt vmcnt(0)
	v_xor_b32_e32 v98, 0x80000000, v9
